# combo7: combo4 (hand-pipelined EpiResGate P4/P6 + attention DMA issued by slack waves + hoisted gain loads) + DPP quad swap in O-epilogue + wave-uniform alpha fast path + K-fragment LDS reads hoisted
# speedup vs baseline: 1.0099x; 1.0099x over previous
; __device__ __forceinline__ void pv_part(f32x16* o, int vb, bf16x8 pa0, bf16x8 pa1, bf16x8 pa2, bf16x8 pa3, f32x16& x0, f32x16& x1, float& m_reg, float& mn, float& alpha) {
;     ...
;     if (__builtin_expect(__all((pmax - m_reg) * SCALE <= THR), 1)) { mn = m_reg; alpha = 1.f; }
;     else { mn = fmaxf(m_reg, pmax); alpha = __builtin_amdgcn_exp2f((m_reg - mn) * C2); m_reg = mn; }
;     const float mnL = -mn * C2;
.LBB0_549:
	s_cmp_eq_u64 s[4:5], exec
	s_cbranch_scc0 .Lalpha_slow0
	s_mov_b64 s[4:5], -1
	v_mov_b32_e32 v209, 1.0
	s_branch .LBB0_553

; #define KSWZ(row, colB) ((row) * 384 + ((colB) ^ (KS3(row) << 4)))
; #define SBAR() __builtin_amdgcn_sched_barrier(0)
; #define ISSUE(X, d0) do { KRD(X##0, ka[(d0) & 3], ((d0) >> 2) * 128); KRD(X##1, ka[(d0) & 3], ((d0) >> 2) * 128 + 32 * KPITCH); } while (0)
; #define USE(X, d0, n) do { KWAIT(n, X##0, X##1); p0 = __builtin_amdgcn_mfma_f32_32x32x16_bf16(X##0, qr[d0], p0, 0, 0, 0); p1 = __builtin_amdgcn_mfma_f32_32x32x16_bf16(X##1, qr[d0], p1, 0, 0, 0); } while (0)
; #define ISSUE(X, d0) do { KRD(X##0, ka[(d0) & 3], ((d0) >> 2) * 128); KRD(X##1, ka[(d0) & 3], ((d0) >> 2) * 128 + 32 * KPITCH); } while (0)
; #define USE(X, d0, n) do { KWAIT(n, X##0, X##1); x0 = __builtin_amdgcn_mfma_f32_32x32x16_bf16(X##0, qr[d0], x0, 0, 0, 0); x1 = __builtin_amdgcn_mfma_f32_32x32x16_bf16(X##1, qr[d0], x1, 0, 0, 0); } while (0)
; __device__ __forceinline__ void qkt_fin(f32x16& x0, f32x16& x1, unsigned kslot, int r32, int hi, const bf16x8* qr,
;                                         f32x16& y0, f32x16& y1, float alpha, float& l_reg, bf16x8& pa0, bf16x8& pa1, bf16x8& pa2, bf16x8& pa3) {
;     unsigned ka[4];
; #pragma unroll
;     for (int dd = 0; dd < 4; ++dd) ka[dd] = kslot + KSWZ(r32, (dd * 16 + hi * 8) * 2);
;     bf16x8 a0, a1, b0, b1, c0, c1;
;     x0 = f32x16{}; x1 = f32x16{};
;     float sacc = 0.f;
;     ...
;     ISSUE(a, 0); ISSUE(b, 1); ISSUE(c, 2); SBAR();
;     USE(a, 0, 4); ISSUE(a, 3); GAP_E(0); USE(b, 1, 4); ISSUE(b, 4); GAP_E(1); USE(c, 2, 4); ISSUE(c, 5); GAP_E(2);
;     USE(a, 3, 4); ISSUE(a, 6); GAP_E(3); USE(b, 4, 4); ISSUE(b, 7); GAP_E(4); USE(c, 5, 4); ISSUE(c, 8); GAP_E(5);
;     USE(a, 6, 4); ISSUE(a, 9); GAP_E(6); USE(b, 7, 4); ISSUE(b, 10); GAP_E(7);
;     USE(c, 8, 4); ISSUE(c, 11); PK4(y0, 0, pa0); sacc += (y1[0] + y1[1]) + (y1[2] + y1[3]); SBAR();
; __device__ __forceinline__ void pv_part(f32x16* o, int vb, bf16x8 pa0, bf16x8 pa1, bf16x8 pa2, bf16x8 pa3, f32x16& x0, f32x16& x1, float& m_reg, float& mn, float& alpha) {
;     ...
;     for (int r = 0; r < 16; ++r) x0[r] = fmaf(x0[r], C2, mnL);
; #pragma unroll
;     for (int r = 0; r < 16; ++r) x1[r] = fmaf(x1[r], C2, mnL);
; #pragma unroll
;     for (int r = 0; r < 6; ++r) x0[r] = __builtin_amdgcn_exp2f(x0[r]);
;     SBAR();
;     asm volatile("s_waitcnt lgkmcnt(0)" ::: "memory"); SBAR(); MM4(B, 3);
; #pragma unroll
;     for (int r = 6; r < 16; ++r) x0[r] = __builtin_amdgcn_exp2f(x0[r]);
.Ldsh0B_done:
.LBB0_557:
	v_cndmask_b32_e64 v173, v144, v189, s[4:5]
	v_mul_f32_e32 v172, 0xbdd53b94, v173
	v_fmamk_f32 v189, v64, 0x3dd53b94, v172
	v_fmamk_f32 v210, v65, 0x3dd53b94, v172
	v_fmamk_f32 v211, v66, 0x3dd53b94, v172
	v_fmamk_f32 v212, v67, 0x3dd53b94, v172
	v_fmamk_f32 v213, v68, 0x3dd53b94, v172
	v_fmamk_f32 v214, v69, 0x3dd53b94, v172
	v_fmamk_f32 v215, v70, 0x3dd53b94, v172
	v_fmamk_f32 v216, v71, 0x3dd53b94, v172
	s_mul_i32 s4, s68, 0x6000
	v_add_u32_e32 v243, s4, v183
	v_add_u32_e32 v240, v243, v184
	v_add_u32_e32 v241, v243, v185
	v_add_u32_e32 v242, v243, v186
	v_add_u32_e32 v243, v243, v187
	ds_read_b128 v[64:67], v240 offset:0
	ds_read_b128 v[68:71], v240 offset:0x3000
	ds_read_b128 v[144:147], v241 offset:0
	ds_read_b128 v[148:151], v241 offset:0x3000
	ds_read_b128 v[152:155], v242 offset:0
	ds_read_b128 v[156:159], v242 offset:0x3000
	v_fmamk_f32 v84, v84, 0x3dd53b94, v172
	v_fmamk_f32 v85, v85, 0x3dd53b94, v172
	v_exp_f32_e32 v226, v84
	v_exp_f32_e32 v227, v85
	v_fmamk_f32 v80, v80, 0x3dd53b94, v172
	v_fmamk_f32 v81, v81, 0x3dd53b94, v172
	v_fmamk_f32 v82, v82, 0x3dd53b94, v172
	v_fmamk_f32 v83, v83, 0x3dd53b94, v172
	v_fmamk_f32 v86, v86, 0x3dd53b94, v172
	v_fmamk_f32 v87, v87, 0x3dd53b94, v172
	v_fmamk_f32 v88, v88, 0x3dd53b94, v172
	v_fmamk_f32 v89, v89, 0x3dd53b94, v172
	v_fmamk_f32 v90, v90, 0x3dd53b94, v172
	v_fmamk_f32 v91, v91, 0x3dd53b94, v172
	v_fmamk_f32 v92, v92, 0x3dd53b94, v172
	v_fmamk_f32 v93, v93, 0x3dd53b94, v172
	v_fmamk_f32 v94, v94, 0x3dd53b94, v172
	v_fmamk_f32 v95, v95, 0x3dd53b94, v172
	v_fmamk_f32 v217, v72, 0x3dd53b94, v172
	v_fmamk_f32 v218, v73, 0x3dd53b94, v172
	v_fmamk_f32 v219, v74, 0x3dd53b94, v172
	v_fmamk_f32 v220, v75, 0x3dd53b94, v172
	v_fmamk_f32 v221, v76, 0x3dd53b94, v172
	v_exp_f32_e32 v222, v80
	v_exp_f32_e32 v223, v81
	v_exp_f32_e32 v224, v82
	v_exp_f32_e32 v225, v83
	v_exp_f32_e32 v228, v86
	v_exp_f32_e32 v229, v87
	v_exp_f32_e32 v230, v88
	v_exp_f32_e32 v231, v89
	v_exp_f32_e32 v232, v90
	v_exp_f32_e32 v233, v91
	v_exp_f32_e32 v234, v92
	v_exp_f32_e32 v235, v93
	v_exp_f32_e32 v236, v94
	v_exp_f32_e32 v237, v95
	v_fmamk_f32 v238, v77, 0x3dd53b94, v172
	v_fmamk_f32 v239, v78, 0x3dd53b94, v172
	v_fmac_f32_e32 v172, 0x3dd53b94, v79
	s_nop 0
	s_waitcnt lgkmcnt(4)
	ds_read_b128 v[162:165], v243 offset:0
	ds_read_b128 v[194:197], v243 offset:0x3000
	v_exp_f32_e32 v244, v210
	v_mfma_f32_32x32x16_bf16 v[80:95], v[64:67], v[140:143], 0
	v_add_f32_e32 v210, 0, v222
	v_exp_f32_e32 v189, v189
	v_add_f32_e32 v210, v223, v210
	v_mfma_f32_32x32x16_bf16 v[64:79], v[68:71], v[140:143], 0
	s_waitcnt lgkmcnt(4)
	v_add_f32_e32 v210, v224, v210
	v_mfma_f32_32x32x16_bf16 v[80:95], v[144:147], v[136:139], v[80:95]
	ds_read_b128 v[144:147], v240 offset:0x80
	v_exp_f32_e32 v245, v211
	v_exp_f32_e32 v246, v212
	v_add_f32_e32 v210, v225, v210
	v_mfma_f32_32x32x16_bf16 v[64:79], v[148:151], v[136:139], v[64:79]
	ds_read_b128 v[148:151], v240 offset:0x3080
	s_waitcnt lgkmcnt(4)
	v_add_f32_e32 v210, v226, v210
	v_mfma_f32_32x32x16_bf16 v[80:95], v[152:155], v[132:135], v[80:95]
	ds_read_b128 v[152:155], v241 offset:0x80
	v_exp_f32_e32 v247, v213
	v_exp_f32_e32 v248, v214
	v_add_f32_e32 v210, v227, v210
	v_mfma_f32_32x32x16_bf16 v[64:79], v[156:159], v[132:135], v[64:79]
	ds_read_b128 v[156:159], v241 offset:0x3080
	s_waitcnt lgkmcnt(4)
	v_add_f32_e32 v210, v228, v210
	v_mfma_f32_32x32x16_bf16 v[80:95], v[162:165], v[128:131], v[80:95]
	ds_read_b128 v[162:165], v242 offset:0x80
	v_exp_f32_e32 v249, v215
	v_exp_f32_e32 v204, v216
	v_add_f32_e32 v210, v229, v210
	v_mfma_f32_32x32x16_bf16 v[64:79], v[194:197], v[128:131], v[64:79]
	ds_read_b128 v[194:197], v242 offset:0x3080
	s_waitcnt lgkmcnt(4)
	v_add_f32_e32 v210, v230, v210
	v_mfma_f32_32x32x16_bf16 v[80:95], v[144:147], v[124:127], v[80:95]
	ds_read_b128 v[144:147], v243 offset:0x80
	v_exp_f32_e32 v193, v217
	v_exp_f32_e32 v250, v218
	v_add_f32_e32 v210, v231, v210
	v_mfma_f32_32x32x16_bf16 v[64:79], v[148:151], v[124:127], v[64:79]
	ds_read_b128 v[148:151], v243 offset:0x3080
	s_waitcnt lgkmcnt(4)
	v_add_f32_e32 v210, v232, v210
	v_mfma_f32_32x32x16_bf16 v[80:95], v[152:155], v[120:123], v[80:95]
	ds_read_b128 v[152:155], v240 offset:0x100
	v_exp_f32_e32 v251, v220
	v_add_f32_e32 v210, v233, v210
	v_mfma_f32_32x32x16_bf16 v[64:79], v[156:159], v[120:123], v[64:79]
	ds_read_b128 v[156:159], v240 offset:0x3100
	v_exp_f32_e32 v240, v219
	s_waitcnt lgkmcnt(4)
	v_add_f32_e32 v210, v234, v210
	v_mfma_f32_32x32x16_bf16 v[80:95], v[162:165], v[116:119], v[80:95]
	ds_read_b128 v[162:165], v241 offset:0x100
	v_exp_f32_e32 v238, v238
	v_add_f32_e32 v218, v235, v210
	v_mfma_f32_32x32x16_bf16 v[64:79], v[194:197], v[116:119], v[64:79]
	ds_read_b128 v[194:197], v241 offset:0x3100
	v_exp_f32_e32 v241, v221
	s_waitcnt lgkmcnt(4)
	ds_read_b128 v[210:213], v242 offset:0x100
	ds_read_b128 v[214:217], v242 offset:0x3100
	v_exp_f32_e32 v239, v239
	v_mfma_f32_32x32x16_bf16 v[80:95], v[144:147], v[112:115], v[80:95]
	v_add_f32_e32 v144, v236, v218
	v_exp_f32_e32 v172, v172
	v_mfma_f32_32x32x16_bf16 v[64:79], v[148:151], v[112:115], v[64:79]
	v_add_f32_e32 v148, v237, v144
	s_waitcnt lgkmcnt(4)
	v_add_f32_e32 v149, v189, v244
	v_mfma_f32_32x32x16_bf16 v[80:95], v[152:155], v[108:111], v[80:95]
	v_add_f32_e32 v150, v245, v246
	v_add_f32_e32 v149, v149, v150
	v_add_f32_e32 v152, v149, v148
	v_mfma_f32_32x32x16_bf16 v[64:79], v[156:159], v[108:111], v[64:79]
	ds_read_b128 v[156:159], v243 offset:0x100
	ds_read_b128 v[218:221], v243 offset:0x3100
	v_cvt_pk_bf16_f32 v144, v222, v223
	v_cvt_pk_bf16_f32 v145, v224, v225
	v_cvt_pk_bf16_f32 v146, v226, v227
	v_cvt_pk_bf16_f32 v147, v228, v229
	s_nop 0
	v_permlane32_swap_b32_e32 v144, v146
	v_permlane32_swap_b32_e32 v145, v147
	s_waitcnt lgkmcnt(4)
; #define SBAR() __builtin_amdgcn_sched_barrier(0)
; #define ISSUE(X, d0) do { KRD(X##0, ka[(d0) & 3], ((d0) >> 2) * 128); KRD(X##1, ka[(d0) & 3], ((d0) >> 2) * 128 + 32 * KPITCH); } while (0)
; #define USE(X, d0, n) do { KWAIT(n, X##0, X##1); p0 = __builtin_amdgcn_mfma_f32_32x32x16_bf16(X##0, qr[d0], p0, 0, 0, 0); p1 = __builtin_amdgcn_mfma_f32_32x32x16_bf16(X##1, qr[d0], p1, 0, 0, 0); } while (0)
; #define ISSUE(X, d0) do { KRD(X##0, ka[(d0) & 3], ((d0) >> 2) * 128); KRD(X##1, ka[(d0) & 3], ((d0) >> 2) * 128 + 32 * KPITCH); } while (0)
; #define USE(X, d0, n) do { KWAIT(n, X##0, X##1); x0 = __builtin_amdgcn_mfma_f32_32x32x16_bf16(X##0, qr[d0], x0, 0, 0, 0); x1 = __builtin_amdgcn_mfma_f32_32x32x16_bf16(X##1, qr[d0], x1, 0, 0, 0); } while (0)
; __device__ __forceinline__ void mask_tile(f32x16& p0, f32x16& p1, int dq) {
;     const float NEG = -__builtin_inff();
; #pragma unroll
;     for (int r = 0; r < 16; ++r) {
;         const int c = (r & 3) + 8 * (r >> 2);
;         if (dq - c < 0) p0[r] = NEG;
;         if (dq - c - 32 < 0) p1[r] = NEG;
;     }
; }
; __device__ __forceinline__ void qkt_fin(f32x16& x0, f32x16& x1, unsigned kslot, int r32, int hi, const bf16x8* qr,
;                                         f32x16& y0, f32x16& y1, float alpha, float& l_reg, bf16x8& pa0, bf16x8& pa1, bf16x8& pa2, bf16x8& pa3) {
;     ...
;     USE(c, 8, 4); ISSUE(c, 11); PK4(y0, 0, pa0); sacc += (y1[0] + y1[1]) + (y1[2] + y1[3]); SBAR();
;     USE(a, 9, 4); PK4(y0, 8, pa1); sacc += (y1[4] + y1[5]) + (y1[6] + y1[7]); SBAR();
;     USE(b, 10, 2); PK4(y1, 0, pa2); sacc += (y1[8] + y1[9]) + (y1[10] + y1[11]); SBAR();
;     USE(c, 11, 0); PK4(y1, 8, pa3); sacc += (y1[12] + y1[13]) + (y1[14] + y1[15]);
;     { auto rr = __builtin_amdgcn_permlane32_swap(__float_as_uint(sacc), __float_as_uint(sacc), false, false);
;       sacc = __uint_as_float(rr[0]) + __uint_as_float(rr[1]); }
;     l_reg = l_reg * alpha + sacc;
	v_cvt_pk_bf16_f32 v148, v230, v231
	v_cvt_pk_bf16_f32 v149, v232, v233
	v_cvt_pk_bf16_f32 v150, v234, v235
	v_cvt_pk_bf16_f32 v151, v236, v237
	v_add_f32_e32 v153, v247, v248
	v_mfma_f32_32x32x16_bf16 v[80:95], v[162:165], v[104:107], v[80:95]
	v_add_f32_e32 v154, v249, v204
	v_permlane32_swap_b32_e32 v148, v150
	v_permlane32_swap_b32_e32 v149, v151
	v_add_f32_e32 v153, v153, v154
	v_add_f32_e32 v162, v153, v152
	v_mfma_f32_32x32x16_bf16 v[64:79], v[194:197], v[104:107], v[64:79]
	s_waitcnt lgkmcnt(2)
	v_cvt_pk_bf16_f32 v152, v189, v244
	v_cvt_pk_bf16_f32 v153, v245, v246
	v_cvt_pk_bf16_f32 v154, v247, v248
	v_cvt_pk_bf16_f32 v155, v249, v204
	v_add_f32_e32 v163, v193, v250
	v_mfma_f32_32x32x16_bf16 v[80:95], v[210:213], v[100:103], v[80:95]
	v_add_f32_e32 v164, v240, v251
	v_permlane32_swap_b32_e32 v152, v154
	v_permlane32_swap_b32_e32 v153, v155
	v_add_f32_e32 v163, v163, v164
	v_add_f32_e32 v162, v163, v162
	v_mfma_f32_32x32x16_bf16 v[64:79], v[214:217], v[100:103], v[64:79]
	s_waitcnt lgkmcnt(0)
	v_add_f32_e32 v163, v241, v238
	v_mfma_f32_32x32x16_bf16 v[80:95], v[156:159], v[96:99], v[80:95]
	v_add_f32_e32 v164, v239, v172
	v_add_f32_e32 v163, v163, v164
	v_add_f32_e32 v226, v163, v162
	v_cvt_pk_bf16_f32 v156, v193, v250
	v_cvt_pk_bf16_f32 v157, v240, v251
	v_cvt_pk_bf16_f32 v158, v241, v238
	v_cvt_pk_bf16_f32 v159, v239, v172
	v_mfma_f32_32x32x16_bf16 v[64:79], v[218:221], v[96:99], v[64:79]
	v_mov_b32_e32 v227, v226
	v_permlane32_swap_b32_e32 v156, v158
	v_permlane32_swap_b32_e32 v157, v159
	v_permlane32_swap_b32_e32 v226, v227
	s_cmp_le_i32 s81, s78
	s_cbranch_scc1 .LBB0_559
	v_cmp_gt_i32_e64 s[64:65], 26, v206
	v_cmp_gt_i32_e64 s[66:67], 27, v206
	v_cmp_gt_i32_e64 s[62:63], 25, v206
	s_and_b64 s[64:65], s[66:67], s[64:65]
	v_cmp_gt_i32_e64 s[60:61], 24, v206
	s_and_b64 s[62:63], s[64:65], s[62:63]
	v_cmp_gt_i32_e64 s[58:59], 19, v206
	s_and_b64 s[60:61], s[62:63], s[60:61]
	v_cmp_gt_i32_e64 s[56:57], 18, v206
	s_and_b64 s[58:59], s[60:61], s[58:59]
	v_cmp_gt_i32_e64 s[54:55], 17, v206
	s_and_b64 s[56:57], s[58:59], s[56:57]
	v_cmp_gt_i32_e64 s[52:53], 16, v206
	s_and_b64 s[54:55], s[56:57], s[54:55]
	v_cmp_gt_i32_e64 s[50:51], 11, v206
	s_and_b64 s[52:53], s[54:55], s[52:53]
	v_cmp_gt_i32_e64 s[48:49], 10, v206
	s_and_b64 s[50:51], s[52:53], s[50:51]
	v_cmp_gt_i32_e64 s[46:47], 9, v206
	s_and_b64 s[48:49], s[50:51], s[48:49]
	v_cmp_gt_i32_e64 s[44:45], 8, v206
	s_and_b64 s[46:47], s[48:49], s[46:47]
	v_cmp_gt_i32_e64 s[42:43], 3, v206
	s_and_b64 s[44:45], s[46:47], s[44:45]
	v_cmp_gt_i32_e64 s[40:41], 2, v206
	s_and_b64 s[42:43], s[44:45], s[42:43]
	v_cmp_gt_i32_e64 s[36:37], 1, v206
	s_and_b64 s[40:41], s[42:43], s[40:41]
	v_cmp_gt_i32_e64 s[34:35], 0, v206
	s_and_b64 s[36:37], s[40:41], s[36:37]
	s_and_b64 s[34:35], s[36:37], s[34:35]
	v_cmp_gt_i32_e64 s[30:31], 58, v206
	v_cndmask_b32_e64 v80, v80, v203, s[34:35]
	v_cmp_gt_i32_e64 s[34:35], 59, v206
	v_cmp_gt_i32_e64 s[28:29], 57, v206
	s_and_b64 s[30:31], s[34:35], s[30:31]
	v_cmp_gt_i32_e64 s[26:27], 56, v206
	s_and_b64 s[28:29], s[30:31], s[28:29]
	v_cmp_gt_i32_e64 s[24:25], 51, v206
	s_and_b64 s[26:27], s[28:29], s[26:27]
	v_cmp_gt_i32_e64 s[22:23], 50, v206
	s_and_b64 s[24:25], s[26:27], s[24:25]
	v_cmp_gt_i32_e64 s[20:21], 49, v206
	s_and_b64 s[22:23], s[24:25], s[22:23]
	v_cmp_gt_i32_e64 s[18:19], 48, v206
	s_and_b64 s[20:21], s[22:23], s[20:21]
	v_cmp_gt_i32_e64 s[16:17], 43, v206
	s_and_b64 s[18:19], s[20:21], s[18:19]
	v_cmp_gt_i32_e64 s[14:15], 42, v206
	s_and_b64 s[16:17], s[18:19], s[16:17]
	v_cmp_gt_i32_e64 s[12:13], 41, v206
	s_and_b64 s[14:15], s[16:17], s[14:15]
	v_cmp_gt_i32_e64 s[10:11], 40, v206
	s_and_b64 s[12:13], s[14:15], s[12:13]
	v_cmp_gt_i32_e64 s[8:9], 35, v206
	s_and_b64 s[10:11], s[12:13], s[10:11]
	v_cmp_gt_i32_e64 s[6:7], 34, v206
	s_and_b64 s[8:9], s[10:11], s[8:9]
	v_cmp_gt_i32_e64 s[4:5], 33, v206
	s_and_b64 s[6:7], s[8:9], s[6:7]
	v_cmp_gt_i32_e32 vcc, 32, v206
	s_and_b64 s[4:5], s[6:7], s[4:5]
	s_and_b64 vcc, s[4:5], vcc
	v_cndmask_b32_e64 v95, v95, v203, s[66:67]
	s_mov_b32 s67, 0x41000000
	v_cndmask_b32_e64 v94, v94, v203, s[64:65]
	v_cndmask_b32_e64 v93, v93, v203, s[62:63]
	v_cndmask_b32_e64 v92, v92, v203, s[60:61]
	v_cndmask_b32_e64 v91, v91, v203, s[58:59]
	v_cndmask_b32_e64 v90, v90, v203, s[56:57]
	v_cndmask_b32_e64 v89, v89, v203, s[54:55]
	v_cndmask_b32_e64 v88, v88, v203, s[52:53]
	v_cndmask_b32_e64 v87, v87, v203, s[50:51]
	v_cndmask_b32_e64 v86, v86, v203, s[48:49]
	v_cndmask_b32_e64 v85, v85, v203, s[46:47]
	v_cndmask_b32_e64 v84, v84, v203, s[44:45]
	v_cndmask_b32_e64 v83, v83, v203, s[42:43]
	v_cndmask_b32_e64 v82, v82, v203, s[40:41]
	v_cndmask_b32_e64 v81, v81, v203, s[36:37]
	v_cndmask_b32_e64 v79, v79, v203, s[34:35]
	v_cndmask_b32_e64 v78, v78, v203, s[30:31]
	v_cndmask_b32_e64 v77, v77, v203, s[28:29]
	v_cndmask_b32_e64 v76, v76, v203, s[26:27]
	v_cndmask_b32_e64 v75, v75, v203, s[24:25]
	v_cndmask_b32_e64 v74, v74, v203, s[22:23]
	v_cndmask_b32_e64 v73, v73, v203, s[20:21]
	v_cndmask_b32_e64 v72, v72, v203, s[18:19]
	v_cndmask_b32_e64 v71, v71, v203, s[16:17]
	v_cndmask_b32_e64 v70, v70, v203, s[14:15]
	v_cndmask_b32_e64 v69, v69, v203, s[12:13]
	v_cndmask_b32_e64 v68, v68, v203, s[10:11]
	v_cndmask_b32_e64 v67, v67, v203, s[8:9]
	v_cndmask_b32_e64 v66, v66, v203, s[6:7]
	v_cndmask_b32_e64 v65, v65, v203, s[4:5]
	v_cndmask_b32_e32 v64, v64, v203, vcc

; __device__ __forceinline__ void pv_part(f32x16* o, int vb, bf16x8 pa0, bf16x8 pa1, bf16x8 pa2, bf16x8 pa3, f32x16& x0, f32x16& x1, float& m_reg, float& mn, float& alpha) {
;     ...
;     if (__builtin_expect(__all((pmax - m_reg) * SCALE <= THR), 1)) { mn = m_reg; alpha = 1.f; }
;     else { mn = fmaxf(m_reg, pmax); alpha = __builtin_amdgcn_exp2f((m_reg - mn) * C2); m_reg = mn; }
;     const float mnL = -mn * C2;
.LBB0_563:
	s_cmp_lg_u64 s[4:5], 0
	s_cbranch_scc0 .Lalpha_slow2
	v_mov_b32_e32 v172, 1.0
	s_branch .LBB0_567

; __device__ __forceinline__ void pv_part(f32x16* o, int vb, bf16x8 pa0, bf16x8 pa1, bf16x8 pa2, bf16x8 pa3, f32x16& x0, f32x16& x1, float& m_reg, float& mn, float& alpha) {
;     ...
;     if (__builtin_expect(__all((pmax - m_reg) * SCALE <= THR), 1)) { mn = m_reg; alpha = 1.f; }
;     else { mn = fmaxf(m_reg, pmax); alpha = __builtin_amdgcn_exp2f((m_reg - mn) * C2); m_reg = mn; }
;     const float mnL = -mn * C2;
.LBB0_716:
	s_cmp_eq_u64 s[4:5], exec
	s_cbranch_scc0 .Lalpha_slow1
	s_mov_b64 s[4:5], -1
	v_mov_b32_e32 v210, 1.0
	s_branch .LBB0_720

; #define KSWZ(row, colB) ((row) * 384 + ((colB) ^ (KS3(row) << 4)))
; #define SBAR() __builtin_amdgcn_sched_barrier(0)
; #define ISSUE(X, d0) do { KRD(X##0, ka[(d0) & 3], ((d0) >> 2) * 128); KRD(X##1, ka[(d0) & 3], ((d0) >> 2) * 128 + 32 * KPITCH); } while (0)
; #define USE(X, d0, n) do { KWAIT(n, X##0, X##1); p0 = __builtin_amdgcn_mfma_f32_32x32x16_bf16(X##0, qr[d0], p0, 0, 0, 0); p1 = __builtin_amdgcn_mfma_f32_32x32x16_bf16(X##1, qr[d0], p1, 0, 0, 0); } while (0)
; #define ISSUE(X, d0) do { KRD(X##0, ka[(d0) & 3], ((d0) >> 2) * 128); KRD(X##1, ka[(d0) & 3], ((d0) >> 2) * 128 + 32 * KPITCH); } while (0)
; #define USE(X, d0, n) do { KWAIT(n, X##0, X##1); x0 = __builtin_amdgcn_mfma_f32_32x32x16_bf16(X##0, qr[d0], x0, 0, 0, 0); x1 = __builtin_amdgcn_mfma_f32_32x32x16_bf16(X##1, qr[d0], x1, 0, 0, 0); } while (0)
; __device__ __forceinline__ void qkt_fin(f32x16& x0, f32x16& x1, unsigned kslot, int r32, int hi, const bf16x8* qr,
;                                         f32x16& y0, f32x16& y1, float alpha, float& l_reg, bf16x8& pa0, bf16x8& pa1, bf16x8& pa2, bf16x8& pa3) {
;     unsigned ka[4];
; #pragma unroll
;     for (int dd = 0; dd < 4; ++dd) ka[dd] = kslot + KSWZ(r32, (dd * 16 + hi * 8) * 2);
;     bf16x8 a0, a1, b0, b1, c0, c1;
;     x0 = f32x16{}; x1 = f32x16{};
;     float sacc = 0.f;
;     ...
;     ISSUE(a, 0); ISSUE(b, 1); ISSUE(c, 2); SBAR();
;     USE(a, 0, 4); ISSUE(a, 3); GAP_E(0); USE(b, 1, 4); ISSUE(b, 4); GAP_E(1); USE(c, 2, 4); ISSUE(c, 5); GAP_E(2);
;     USE(a, 3, 4); ISSUE(a, 6); GAP_E(3); USE(b, 4, 4); ISSUE(b, 7); GAP_E(4); USE(c, 5, 4); ISSUE(c, 8); GAP_E(5);
;     USE(a, 6, 4); ISSUE(a, 9); GAP_E(6); USE(b, 7, 4); ISSUE(b, 10); GAP_E(7);
;     USE(c, 8, 4); ISSUE(c, 11); PK4(y0, 0, pa0); sacc += (y1[0] + y1[1]) + (y1[2] + y1[3]); SBAR();
; __device__ __forceinline__ void pv_part(f32x16* o, int vb, bf16x8 pa0, bf16x8 pa1, bf16x8 pa2, bf16x8 pa3, f32x16& x0, f32x16& x1, float& m_reg, float& mn, float& alpha) {
;     ...
;     for (int r = 0; r < 16; ++r) x0[r] = fmaf(x0[r], C2, mnL);
; #pragma unroll
;     for (int r = 0; r < 16; ++r) x1[r] = fmaf(x1[r], C2, mnL);
; #pragma unroll
;     for (int r = 0; r < 6; ++r) x0[r] = __builtin_amdgcn_exp2f(x0[r]);
;     SBAR();
;     asm volatile("s_waitcnt lgkmcnt(0)" ::: "memory"); SBAR(); MM4(B, 3);
; #pragma unroll
;     for (int r = 6; r < 16; ++r) x0[r] = __builtin_amdgcn_exp2f(x0[r]);
.Ldsh1B_done:
.LBB0_724:
	v_cndmask_b32_e64 v173, v144, v189, s[4:5]
	v_mul_f32_e32 v172, 0xbdd53b94, v173
	v_fmamk_f32 v189, v64, 0x3dd53b94, v172
	v_fmamk_f32 v193, v65, 0x3dd53b94, v172
	v_fmamk_f32 v204, v66, 0x3dd53b94, v172
	v_fmamk_f32 v211, v67, 0x3dd53b94, v172
	v_fmamk_f32 v212, v68, 0x3dd53b94, v172
	v_fmamk_f32 v213, v69, 0x3dd53b94, v172
	v_fmamk_f32 v214, v70, 0x3dd53b94, v172
	v_fmamk_f32 v215, v71, 0x3dd53b94, v172
	s_mul_i32 s4, s77, 0x6000
	v_add_u32_e32 v242, s4, v184
	v_add_u32_e32 v223, v242, v185
	v_add_u32_e32 v240, v242, v186
	v_add_u32_e32 v241, v242, v187
	v_add_u32_e32 v242, v242, v188
	ds_read_b128 v[64:67], v223 offset:0
	ds_read_b128 v[68:71], v223 offset:0x3000
	ds_read_b128 v[144:147], v240 offset:0
	ds_read_b128 v[148:151], v240 offset:0x3000
	ds_read_b128 v[152:155], v241 offset:0
	ds_read_b128 v[156:159], v241 offset:0x3000
	v_fmamk_f32 v83, v83, 0x3dd53b94, v172
	v_fmamk_f32 v84, v84, 0x3dd53b94, v172
	v_exp_f32_e32 v227, v83
	v_exp_f32_e32 v228, v84
	v_fmamk_f32 v80, v80, 0x3dd53b94, v172
	v_fmamk_f32 v81, v81, 0x3dd53b94, v172
	v_fmamk_f32 v82, v82, 0x3dd53b94, v172
	v_fmamk_f32 v85, v85, 0x3dd53b94, v172
	v_fmamk_f32 v86, v86, 0x3dd53b94, v172
	v_fmamk_f32 v87, v87, 0x3dd53b94, v172
	v_fmamk_f32 v88, v88, 0x3dd53b94, v172
	v_fmamk_f32 v89, v89, 0x3dd53b94, v172
	v_fmamk_f32 v90, v90, 0x3dd53b94, v172
	v_fmamk_f32 v91, v91, 0x3dd53b94, v172
	v_fmamk_f32 v92, v92, 0x3dd53b94, v172
	v_fmamk_f32 v93, v93, 0x3dd53b94, v172
	v_fmamk_f32 v94, v94, 0x3dd53b94, v172
	v_fmamk_f32 v95, v95, 0x3dd53b94, v172
	v_fmamk_f32 v216, v72, 0x3dd53b94, v172
	v_fmamk_f32 v217, v73, 0x3dd53b94, v172
	v_fmamk_f32 v218, v74, 0x3dd53b94, v172
	v_fmamk_f32 v219, v75, 0x3dd53b94, v172
	v_fmamk_f32 v220, v76, 0x3dd53b94, v172
	v_exp_f32_e32 v224, v80
	v_exp_f32_e32 v225, v81
	v_exp_f32_e32 v226, v82
	v_exp_f32_e32 v229, v85
	v_exp_f32_e32 v230, v86
	v_exp_f32_e32 v231, v87
	v_exp_f32_e32 v232, v88
	v_exp_f32_e32 v233, v89
	v_exp_f32_e32 v234, v90
	v_exp_f32_e32 v235, v91
	v_exp_f32_e32 v236, v92
	v_exp_f32_e32 v237, v93
	v_exp_f32_e32 v238, v94
	v_exp_f32_e32 v239, v95
	v_fmamk_f32 v221, v77, 0x3dd53b94, v172
	v_fmamk_f32 v222, v78, 0x3dd53b94, v172
	v_fmac_f32_e32 v172, 0x3dd53b94, v79
	s_nop 0
	s_waitcnt lgkmcnt(4)
	ds_read_b128 v[162:165], v242 offset:0
	ds_read_b128 v[194:197], v242 offset:0x3000
	v_add_f32_e32 v243, 0, v224
	v_mfma_f32_32x32x16_bf16 v[80:95], v[64:67], v[140:143], 0
	v_exp_f32_e32 v189, v189
	v_exp_f32_e32 v193, v193
	v_add_f32_e32 v243, v225, v243
	v_mfma_f32_32x32x16_bf16 v[64:79], v[68:71], v[140:143], 0
	s_waitcnt lgkmcnt(4)
	v_add_f32_e32 v243, v226, v243
	v_mfma_f32_32x32x16_bf16 v[80:95], v[144:147], v[136:139], v[80:95]
	ds_read_b128 v[144:147], v223 offset:0x80
	v_exp_f32_e32 v204, v204
	v_exp_f32_e32 v211, v211
	v_add_f32_e32 v243, v227, v243
	v_mfma_f32_32x32x16_bf16 v[64:79], v[148:151], v[136:139], v[64:79]
	ds_read_b128 v[148:151], v223 offset:0x3080
	s_waitcnt lgkmcnt(4)
	v_exp_f32_e32 v244, v212
	v_mfma_f32_32x32x16_bf16 v[80:95], v[152:155], v[132:135], v[80:95]
	ds_read_b128 v[152:155], v240 offset:0x80
	v_add_f32_e32 v212, v228, v243
	v_exp_f32_e32 v245, v213
	v_add_f32_e32 v212, v229, v212
	v_mfma_f32_32x32x16_bf16 v[64:79], v[156:159], v[132:135], v[64:79]
	ds_read_b128 v[156:159], v240 offset:0x3080
	s_waitcnt lgkmcnt(4)
	v_add_f32_e32 v212, v230, v212
	v_mfma_f32_32x32x16_bf16 v[80:95], v[162:165], v[128:131], v[80:95]
	ds_read_b128 v[162:165], v241 offset:0x80
	v_exp_f32_e32 v243, v214
	v_exp_f32_e32 v246, v215
	v_add_f32_e32 v212, v231, v212
	v_mfma_f32_32x32x16_bf16 v[64:79], v[194:197], v[128:131], v[64:79]
	ds_read_b128 v[194:197], v241 offset:0x3080
	s_waitcnt lgkmcnt(4)
	v_add_f32_e32 v212, v232, v212
	v_mfma_f32_32x32x16_bf16 v[80:95], v[144:147], v[124:127], v[80:95]
	ds_read_b128 v[144:147], v242 offset:0x80
	v_exp_f32_e32 v247, v216
	v_exp_f32_e32 v248, v217
	v_add_f32_e32 v212, v233, v212
	v_mfma_f32_32x32x16_bf16 v[64:79], v[148:151], v[124:127], v[64:79]
	ds_read_b128 v[148:151], v242 offset:0x3080
	s_waitcnt lgkmcnt(4)
	v_add_f32_e32 v212, v234, v212
	v_mfma_f32_32x32x16_bf16 v[80:95], v[152:155], v[120:123], v[80:95]
	ds_read_b128 v[152:155], v223 offset:0x100
	v_exp_f32_e32 v249, v218
	v_exp_f32_e32 v250, v219
	v_add_f32_e32 v212, v235, v212
	v_mfma_f32_32x32x16_bf16 v[64:79], v[156:159], v[120:123], v[64:79]
	ds_read_b128 v[156:159], v223 offset:0x3100
	s_waitcnt lgkmcnt(4)
	v_add_f32_e32 v212, v236, v212
	v_mfma_f32_32x32x16_bf16 v[80:95], v[162:165], v[116:119], v[80:95]
	ds_read_b128 v[162:165], v240 offset:0x100
	v_exp_f32_e32 v251, v221
	v_mfma_f32_32x32x16_bf16 v[64:79], v[194:197], v[116:119], v[64:79]
	ds_read_b128 v[194:197], v240 offset:0x3100
	v_exp_f32_e32 v240, v220
	v_add_f32_e32 v220, v237, v212
	s_waitcnt lgkmcnt(4)
	ds_read_b128 v[212:215], v241 offset:0x100
	ds_read_b128 v[216:219], v241 offset:0x3100
	v_exp_f32_e32 v241, v222
	v_mfma_f32_32x32x16_bf16 v[80:95], v[144:147], v[112:115], v[80:95]
	v_add_f32_e32 v144, v238, v220
	v_exp_f32_e32 v172, v172
	v_mfma_f32_32x32x16_bf16 v[64:79], v[148:151], v[112:115], v[64:79]
	v_add_f32_e32 v148, v239, v144
	s_waitcnt lgkmcnt(4)
	v_add_f32_e32 v149, v189, v193
	v_mfma_f32_32x32x16_bf16 v[80:95], v[152:155], v[108:111], v[80:95]
	v_add_f32_e32 v150, v204, v211
	v_add_f32_e32 v149, v149, v150
	v_add_f32_e32 v152, v149, v148
	v_mfma_f32_32x32x16_bf16 v[64:79], v[156:159], v[108:111], v[64:79]
	ds_read_b128 v[156:159], v242 offset:0x100
	ds_read_b128 v[220:223], v242 offset:0x3100
	v_cvt_pk_bf16_f32 v144, v224, v225
	v_cvt_pk_bf16_f32 v145, v226, v227
	v_cvt_pk_bf16_f32 v146, v228, v229
	v_cvt_pk_bf16_f32 v147, v230, v231
	s_nop 0
	v_permlane32_swap_b32_e32 v144, v146
	v_permlane32_swap_b32_e32 v145, v147
	s_waitcnt lgkmcnt(4)
; #define SBAR() __builtin_amdgcn_sched_barrier(0)
; #define ISSUE(X, d0) do { KRD(X##0, ka[(d0) & 3], ((d0) >> 2) * 128); KRD(X##1, ka[(d0) & 3], ((d0) >> 2) * 128 + 32 * KPITCH); } while (0)
; #define USE(X, d0, n) do { KWAIT(n, X##0, X##1); p0 = __builtin_amdgcn_mfma_f32_32x32x16_bf16(X##0, qr[d0], p0, 0, 0, 0); p1 = __builtin_amdgcn_mfma_f32_32x32x16_bf16(X##1, qr[d0], p1, 0, 0, 0); } while (0)
; #define ISSUE(X, d0) do { KRD(X##0, ka[(d0) & 3], ((d0) >> 2) * 128); KRD(X##1, ka[(d0) & 3], ((d0) >> 2) * 128 + 32 * KPITCH); } while (0)
; #define USE(X, d0, n) do { KWAIT(n, X##0, X##1); x0 = __builtin_amdgcn_mfma_f32_32x32x16_bf16(X##0, qr[d0], x0, 0, 0, 0); x1 = __builtin_amdgcn_mfma_f32_32x32x16_bf16(X##1, qr[d0], x1, 0, 0, 0); } while (0)
; __device__ __forceinline__ void mask_tile(f32x16& p0, f32x16& p1, int dq) {
;     const float NEG = -__builtin_inff();
; #pragma unroll
;     for (int r = 0; r < 16; ++r) {
;         const int c = (r & 3) + 8 * (r >> 2);
;         if (dq - c < 0) p0[r] = NEG;
;         if (dq - c - 32 < 0) p1[r] = NEG;
;     }
; }
; __device__ __forceinline__ void qkt_fin(f32x16& x0, f32x16& x1, unsigned kslot, int r32, int hi, const bf16x8* qr,
;                                         f32x16& y0, f32x16& y1, float alpha, float& l_reg, bf16x8& pa0, bf16x8& pa1, bf16x8& pa2, bf16x8& pa3) {
;     ...
;     USE(c, 8, 4); ISSUE(c, 11); PK4(y0, 0, pa0); sacc += (y1[0] + y1[1]) + (y1[2] + y1[3]); SBAR();
;     USE(a, 9, 4); PK4(y0, 8, pa1); sacc += (y1[4] + y1[5]) + (y1[6] + y1[7]); SBAR();
;     USE(b, 10, 2); PK4(y1, 0, pa2); sacc += (y1[8] + y1[9]) + (y1[10] + y1[11]); SBAR();
;     USE(c, 11, 0); PK4(y1, 8, pa3); sacc += (y1[12] + y1[13]) + (y1[14] + y1[15]);
;     { auto rr = __builtin_amdgcn_permlane32_swap(__float_as_uint(sacc), __float_as_uint(sacc), false, false);
;       sacc = __uint_as_float(rr[0]) + __uint_as_float(rr[1]); }
;     l_reg = l_reg * alpha + sacc;
	v_cvt_pk_bf16_f32 v148, v232, v233
	v_cvt_pk_bf16_f32 v149, v234, v235
	v_cvt_pk_bf16_f32 v150, v236, v237
	v_cvt_pk_bf16_f32 v151, v238, v239
	v_add_f32_e32 v153, v244, v245
	v_mfma_f32_32x32x16_bf16 v[80:95], v[162:165], v[104:107], v[80:95]
	v_add_f32_e32 v154, v243, v246
	v_permlane32_swap_b32_e32 v148, v150
	v_permlane32_swap_b32_e32 v149, v151
	v_add_f32_e32 v153, v153, v154
	v_add_f32_e32 v162, v153, v152
	v_mfma_f32_32x32x16_bf16 v[64:79], v[194:197], v[104:107], v[64:79]
	s_waitcnt lgkmcnt(2)
	v_cvt_pk_bf16_f32 v152, v189, v193
	v_cvt_pk_bf16_f32 v153, v204, v211
	v_cvt_pk_bf16_f32 v154, v244, v245
	v_cvt_pk_bf16_f32 v155, v243, v246
	v_add_f32_e32 v163, v247, v248
	v_mfma_f32_32x32x16_bf16 v[80:95], v[212:215], v[100:103], v[80:95]
	v_add_f32_e32 v164, v249, v250
	v_permlane32_swap_b32_e32 v152, v154
	v_permlane32_swap_b32_e32 v153, v155
	v_add_f32_e32 v163, v163, v164
	v_add_f32_e32 v162, v163, v162
	v_mfma_f32_32x32x16_bf16 v[64:79], v[216:219], v[100:103], v[64:79]
	s_waitcnt lgkmcnt(0)
	v_add_f32_e32 v163, v240, v251
	v_mfma_f32_32x32x16_bf16 v[80:95], v[156:159], v[96:99], v[80:95]
	v_add_f32_e32 v164, v241, v172
	v_add_f32_e32 v163, v163, v164
	v_add_f32_e32 v227, v163, v162
	v_cvt_pk_bf16_f32 v156, v247, v248
	v_cvt_pk_bf16_f32 v157, v249, v250
	v_cvt_pk_bf16_f32 v158, v240, v251
	v_cvt_pk_bf16_f32 v159, v241, v172
	v_mfma_f32_32x32x16_bf16 v[64:79], v[220:223], v[96:99], v[64:79]
	v_mov_b32_e32 v228, v227
	v_permlane32_swap_b32_e32 v156, v158
	v_permlane32_swap_b32_e32 v157, v159
	v_permlane32_swap_b32_e32 v227, v228
	s_cmp_le_i32 s96, s86
	s_cbranch_scc1 .LBB0_726
	v_cmp_gt_i32_e64 s[64:65], 26, v207
	v_cmp_gt_i32_e64 s[66:67], 27, v207
	v_cmp_gt_i32_e64 s[62:63], 25, v207
	s_and_b64 s[64:65], s[66:67], s[64:65]
	v_cmp_gt_i32_e64 s[60:61], 24, v207
	s_and_b64 s[62:63], s[64:65], s[62:63]
	v_cmp_gt_i32_e64 s[58:59], 19, v207
	s_and_b64 s[60:61], s[62:63], s[60:61]
	v_cmp_gt_i32_e64 s[56:57], 18, v207
	s_and_b64 s[58:59], s[60:61], s[58:59]
	v_cmp_gt_i32_e64 s[54:55], 17, v207
	s_and_b64 s[56:57], s[58:59], s[56:57]
	v_cmp_gt_i32_e64 s[52:53], 16, v207
	s_and_b64 s[54:55], s[56:57], s[54:55]
	v_cmp_gt_i32_e64 s[50:51], 11, v207
	s_and_b64 s[52:53], s[54:55], s[52:53]
	v_cmp_gt_i32_e64 s[48:49], 10, v207
	s_and_b64 s[50:51], s[52:53], s[50:51]
	v_cmp_gt_i32_e64 s[46:47], 9, v207
	s_and_b64 s[48:49], s[50:51], s[48:49]
	v_cmp_gt_i32_e64 s[44:45], 8, v207
	s_and_b64 s[46:47], s[48:49], s[46:47]
	v_cmp_gt_i32_e64 s[42:43], 3, v207
	s_and_b64 s[44:45], s[46:47], s[44:45]
	v_cmp_gt_i32_e64 s[40:41], 2, v207
	s_and_b64 s[42:43], s[44:45], s[42:43]
	v_cmp_gt_i32_e64 s[36:37], 1, v207
	s_and_b64 s[40:41], s[42:43], s[40:41]
	v_cmp_gt_i32_e64 s[34:35], 0, v207
	s_and_b64 s[36:37], s[40:41], s[36:37]
	s_and_b64 s[34:35], s[36:37], s[34:35]
	v_cmp_gt_i32_e64 s[30:31], 58, v207
	v_cndmask_b32_e64 v80, v80, v203, s[34:35]
	v_cmp_gt_i32_e64 s[34:35], 59, v207
	v_cmp_gt_i32_e64 s[28:29], 57, v207
	s_and_b64 s[30:31], s[34:35], s[30:31]
	v_cmp_gt_i32_e64 s[26:27], 56, v207
	s_and_b64 s[28:29], s[30:31], s[28:29]
	v_cmp_gt_i32_e64 s[24:25], 51, v207
	s_and_b64 s[26:27], s[28:29], s[26:27]
	v_cmp_gt_i32_e64 s[22:23], 50, v207
	s_and_b64 s[24:25], s[26:27], s[24:25]
	v_cmp_gt_i32_e64 s[20:21], 49, v207
	s_and_b64 s[22:23], s[24:25], s[22:23]
	v_cmp_gt_i32_e64 s[18:19], 48, v207
	s_and_b64 s[20:21], s[22:23], s[20:21]
	v_cmp_gt_i32_e64 s[16:17], 43, v207
	s_and_b64 s[18:19], s[20:21], s[18:19]
	v_cmp_gt_i32_e64 s[14:15], 42, v207
	s_and_b64 s[16:17], s[18:19], s[16:17]
	v_cmp_gt_i32_e64 s[12:13], 41, v207
	s_and_b64 s[14:15], s[16:17], s[14:15]
	v_cmp_gt_i32_e64 s[10:11], 40, v207
	s_and_b64 s[12:13], s[14:15], s[12:13]
	v_cmp_gt_i32_e64 s[8:9], 35, v207
	s_and_b64 s[10:11], s[12:13], s[10:11]
	v_cmp_gt_i32_e64 s[6:7], 34, v207
	s_and_b64 s[8:9], s[10:11], s[8:9]
	v_cmp_gt_i32_e64 s[4:5], 33, v207
	s_and_b64 s[6:7], s[8:9], s[6:7]
	v_cmp_gt_i32_e32 vcc, 32, v207
	s_and_b64 s[4:5], s[6:7], s[4:5]
	s_and_b64 vcc, s[4:5], vcc
	v_cndmask_b32_e64 v95, v95, v203, s[66:67]
	s_mov_b32 s67, 0x41000000
	v_cndmask_b32_e64 v94, v94, v203, s[64:65]
	v_cndmask_b32_e64 v93, v93, v203, s[62:63]
	v_cndmask_b32_e64 v92, v92, v203, s[60:61]
	v_cndmask_b32_e64 v91, v91, v203, s[58:59]
	v_cndmask_b32_e64 v90, v90, v203, s[56:57]
	v_cndmask_b32_e64 v89, v89, v203, s[54:55]
	v_cndmask_b32_e64 v88, v88, v203, s[52:53]
	v_cndmask_b32_e64 v87, v87, v203, s[50:51]
	v_cndmask_b32_e64 v86, v86, v203, s[48:49]
	v_cndmask_b32_e64 v85, v85, v203, s[46:47]
	v_cndmask_b32_e64 v84, v84, v203, s[44:45]
	v_cndmask_b32_e64 v83, v83, v203, s[42:43]
	v_cndmask_b32_e64 v82, v82, v203, s[40:41]
	v_cndmask_b32_e64 v81, v81, v203, s[36:37]
	v_cndmask_b32_e64 v79, v79, v203, s[34:35]
	v_cndmask_b32_e64 v78, v78, v203, s[30:31]
	v_cndmask_b32_e64 v77, v77, v203, s[28:29]
	v_cndmask_b32_e64 v76, v76, v203, s[26:27]
	v_cndmask_b32_e64 v75, v75, v203, s[24:25]
	v_cndmask_b32_e64 v74, v74, v203, s[22:23]
	v_cndmask_b32_e64 v73, v73, v203, s[20:21]
	v_cndmask_b32_e64 v72, v72, v203, s[18:19]
	v_cndmask_b32_e64 v71, v71, v203, s[16:17]
	v_cndmask_b32_e64 v70, v70, v203, s[14:15]
	v_cndmask_b32_e64 v69, v69, v203, s[12:13]
	v_cndmask_b32_e64 v68, v68, v203, s[10:11]
	v_cndmask_b32_e64 v67, v67, v203, s[8:9]
	v_cndmask_b32_e64 v66, v66, v203, s[6:7]
	v_cndmask_b32_e64 v65, v65, v203, s[4:5]
	v_cndmask_b32_e32 v64, v64, v203, vcc
